# speedup vs baseline: 1.0125x; 1.0026x over previous
.LBB0_858:
	s_waitcnt lgkmcnt(0)
	s_barrier
	s_and_saveexec_b64 s[48:49], s[2:3]
	s_cbranch_execz .LBB0_865
	v_mov_b32_e32 v9, 0
	s_and_saveexec_b64 s[50:51], s[78:79]
	s_cbranch_execz .LBB0_863
	v_cndmask_b32_e64 v8, 0, 1, s[82:83]
	v_lshl_add_u32 v8, v8, 10, v157
	ds_read_b32 v11, v8
	ds_read_b32 v12, v8 offset:256
	ds_read_b32 v13, v8 offset:512
	v_mov_b32_e32 v9, 0
	v_cmp_lt_u32_e64 s[34:35], 1, v125
	v_cmp_lt_u32_e64 s[52:53], 2, v125
	s_waitcnt lgkmcnt(0)
	v_add_f32_e32 v9, v9, v11
	v_add_f32_e32 v12, v9, v12
	v_cndmask_b32_e64 v9, v9, v12, s[34:35]
	v_add_f32_e32 v13, v9, v13
	v_cndmask_b32_e64 v9, v9, v13, s[52:53]
